# peer_convert: next row's loads prefetched one iteration ahead (on top of 3-deep L6 epilogue)
# baseline (speedup 1.0000x reference)
.LBB0_1190:
	s_mov_b64 s[46:47], 0x1000
	s_mov_b32 s84, 0x800000
	s_or_b64 exec, exec, s[2:3]
	v_mov_b32_e32 v0, v172
	v_readlane_b32 s20, v247, 37
	v_ashrrev_i32_e32 v1, 6, v0
	v_readlane_b32 s18, v247, 39
	v_add_u32_e32 v6, s24, v1
	s_mov_b32 s1, 0x8000
	v_readlane_b32 s21, v247, 38
	v_readlane_b32 s19, v247, 40
	s_mov_b32 s17, 0x3000000
	s_mov_b32 s14, 0x3010000
	s_mov_b32 s15, 0x3020000
	s_mov_b32 s16, 0x3030000
	s_movk_i32 s22, 0x2000
	v_cmp_gt_i32_e32 vcc, s1, v6
	s_and_saveexec_b64 s[6:7], vcc
	s_movk_i32 s30, 0x2fff
	s_cbranch_execz .LBB0_1195
	v_and_b32_e32 v3, 63, v0
	v_and_b32_e32 v0, 64, v191
	v_add_u32_e32 v0, 64, v0
	v_xor_b32_e32 v1, 32, v191
	v_cmp_lt_i32_e32 vcc, v1, v0
	s_ashr_i32 s1, s0, 31
	v_lshlrev_b32_e32 v2, 4, v3
	v_cndmask_b32_e32 v1, v191, v1, vcc
	v_lshlrev_b32_e32 v7, 2, v1
	v_xor_b32_e32 v1, 16, v191
	v_cmp_lt_i32_e32 vcc, v1, v0
	s_lshl_b64 s[8:9], s[0:1], 26
	v_cmp_eq_u32_e64 s[2:3], 0, v3
	v_cndmask_b32_e32 v1, v191, v1, vcc
	v_lshlrev_b32_e32 v8, 2, v1
	v_xor_b32_e32 v1, 8, v191
	v_cmp_lt_i32_e32 vcc, v1, v0
	s_mov_b64 s[10:11], 0
	v_lshlrev_b32_e32 v2, 2, v2
	v_cndmask_b32_e32 v1, v191, v1, vcc
	v_lshlrev_b32_e32 v9, 2, v1
	v_xor_b32_e32 v1, 4, v191
	v_cmp_lt_i32_e32 vcc, v1, v0
	s_nop 1
	v_cndmask_b32_e32 v1, v191, v1, vcc
	v_lshlrev_b32_e32 v10, 2, v1
	v_xor_b32_e32 v1, 2, v191
	v_cmp_lt_i32_e32 vcc, v1, v0
	s_nop 1
	v_cndmask_b32_e32 v1, v191, v1, vcc
	v_lshlrev_b32_e32 v11, 2, v1
	v_xor_b32_e32 v1, 1, v191
	v_cmp_lt_i32_e32 vcc, v1, v0
	s_nop 1
	v_cndmask_b32_e32 v0, v191, v1, vcc
	v_lshlrev_b32_e32 v12, 2, v0
	v_lshlrev_b32_e32 v0, 3, v3
	v_mov_b32_e32 v1, v149
	s_movk_i32 s0, 0x4000
	v_mov_b32_e32 v90, v6
	v_cmp_gt_u32_e64 s[12:13], s0, v90
	v_mov_b32_e32 v91, s29
	v_mov_b32_e32 v92, s27
	s_nop 0
	v_cndmask_b32_e64 v95, v91, v92, s[12:13]
	v_mov_b32_e32 v91, s28
	v_mov_b32_e32 v92, s26
	v_and_b32_e32 v93, 0x3fff, v90
	v_cndmask_b32_e64 v94, v91, v92, s[12:13]
	v_lshl_add_u64 v[94:95], v[94:95], 0, s[8:9]
	v_lshlrev_b32_e32 v112, 12, v93
	v_mov_b32_e32 v113, 0
	v_lshl_add_u64 v[94:95], v[94:95], 0, v[112:113]
	v_mov_b32_e32 v112, v2
	v_lshl_add_u64 v[94:95], v[94:95], 0, v[112:113]
	global_load_dwordx4 v[96:99], v[94:95], off offset:48
	global_load_dwordx4 v[100:103], v[94:95], off offset:32
	global_load_dwordx4 v[104:107], v[94:95], off offset:16
	global_load_dwordx4 v[108:111], v[94:95], off
	s_waitcnt vmcnt(0)
	v_mov_b32_e32 v14, v96
	v_mov_b32_e32 v15, v97
	v_mov_b32_e32 v16, v98
	v_mov_b32_e32 v17, v99
	v_mov_b32_e32 v18, v100
	v_mov_b32_e32 v19, v101
	v_mov_b32_e32 v20, v102
	v_mov_b32_e32 v21, v103
	v_mov_b32_e32 v22, v104
	v_mov_b32_e32 v23, v105
	v_mov_b32_e32 v24, v106
	v_mov_b32_e32 v25, v107
	v_mov_b32_e32 v26, v108
	v_mov_b32_e32 v27, v109
	v_mov_b32_e32 v28, v110
	v_mov_b32_e32 v29, v111
	s_branch .LBB0_1193
.LBB0_1192:
	s_or_b64 exec, exec, s[0:1]
	s_waitcnt vmcnt(2)
	v_mov_b32_e32 v14, v96
	v_mov_b32_e32 v15, v97
	v_mov_b32_e32 v16, v98
	v_mov_b32_e32 v17, v99
	v_mov_b32_e32 v18, v100
	v_mov_b32_e32 v19, v101
	v_mov_b32_e32 v20, v102
	v_mov_b32_e32 v21, v103
	v_mov_b32_e32 v22, v104
	v_mov_b32_e32 v23, v105
	v_mov_b32_e32 v24, v106
	v_mov_b32_e32 v25, v107
	v_mov_b32_e32 v26, v108
	v_mov_b32_e32 v27, v109
	v_mov_b32_e32 v28, v110
	v_mov_b32_e32 v29, v111
	v_add_u32_e32 v6, s23, v6
	v_cmp_lt_i32_e32 vcc, s52, v6
	s_or_b64 s[10:11], vcc, s[10:11]
	s_andn2_b64 exec, exec, s[10:11]
	s_cbranch_execz .LBB0_1195
.LBB0_1193:
	s_movk_i32 s0, 0x4000
	v_cmp_gt_u32_e64 s[4:5], s0, v6
	v_and_b32_e32 v13, 0x3fff, v6
	v_add_u32_e32 v90, s23, v6
	v_min_i32_e32 v90, s52, v90
	v_cmp_gt_u32_e64 s[12:13], s0, v90
	v_mov_b32_e32 v91, s29
	v_mov_b32_e32 v92, s27
	s_nop 0
	v_cndmask_b32_e64 v95, v91, v92, s[12:13]
	v_mov_b32_e32 v91, s28
	v_mov_b32_e32 v92, s26
	v_and_b32_e32 v93, 0x3fff, v90
	v_cndmask_b32_e64 v94, v91, v92, s[12:13]
	v_lshl_add_u64 v[94:95], v[94:95], 0, s[8:9]
	v_lshlrev_b32_e32 v112, 12, v93
	v_mov_b32_e32 v113, 0
	v_lshl_add_u64 v[94:95], v[94:95], 0, v[112:113]
	v_mov_b32_e32 v112, v2
	v_lshl_add_u64 v[94:95], v[94:95], 0, v[112:113]
	global_load_dwordx4 v[96:99], v[94:95], off offset:48
	global_load_dwordx4 v[100:103], v[94:95], off offset:32
	global_load_dwordx4 v[104:107], v[94:95], off offset:16
	global_load_dwordx4 v[108:111], v[94:95], off
	v_cndmask_b32_e64 v148, v202, v203, s[4:5]
	s_waitcnt vmcnt(4)
	v_max_f32_e64 v32, |v16|, |v16|
	v_max_f32_e64 v30, |v18|, |v18|
	v_max_f32_e64 v5, |v24|, |v24|
	v_max_f32_e64 v3, |v29|, |v29|
	v_max_f32_e64 v4, |v28|, |v28|
	v_max_f32_e32 v3, v4, v3
	v_max_f32_e64 v4, |v25|, |v25|
	v_max_f32_e32 v4, v5, v4
	v_max_f32_e64 v5, |v19|, |v19|
	v_max_f32_e32 v5, v30, v5
	v_max_f32_e64 v30, |v21|, |v21|
	v_max_f32_e64 v31, |v20|, |v20|
	v_max_f32_e32 v30, v31, v30
	v_max_f32_e64 v31, |v17|, |v17|
	v_max_f32_e32 v31, v32, v31
	v_max3_f32 v31, |v14|, |v15|, v31
	v_max3_f32 v3, |v26|, |v27|, v3
	v_max3_f32 v4, |v22|, |v23|, v4
	v_max3_f32 v5, v5, v30, v31
	v_max3_f32 v3, v3, v4, v5
	ds_bpermute_b32 v4, v7, v3
	s_waitcnt lgkmcnt(0)
	v_max_f32_e32 v4, v4, v4
	v_max_f32_e32 v3, v3, v4
	ds_bpermute_b32 v4, v8, v3
	s_waitcnt lgkmcnt(0)
	v_max_f32_e32 v4, v4, v4
	v_max_f32_e32 v3, v3, v4
	ds_bpermute_b32 v4, v9, v3
	s_waitcnt lgkmcnt(0)
	v_max_f32_e32 v4, v4, v4
	v_max_f32_e32 v3, v3, v4
	ds_bpermute_b32 v4, v10, v3
	s_waitcnt lgkmcnt(0)
	v_max_f32_e32 v4, v4, v4
	v_max_f32_e32 v3, v3, v4
	ds_bpermute_b32 v4, v11, v3
	s_waitcnt lgkmcnt(0)
	v_max_f32_e32 v4, v4, v4
	v_max_f32_e32 v3, v3, v4
	ds_bpermute_b32 v4, v12, v3
	s_waitcnt lgkmcnt(0)
	v_max_f32_e32 v4, v4, v4
	v_max_f32_e32 v3, v3, v4
	v_div_scale_f32 v4, s[12:13], v3, v3, s37
	v_rcp_f32_e32 v5, v4
	v_cmp_lt_f32_e64 s[0:1], 0, v3
	v_fma_f32 v30, -v4, v5, 1.0
	v_fmac_f32_e32 v5, v30, v5
	v_div_scale_f32 v30, vcc, s37, v3, s37
	v_mul_f32_e32 v31, v30, v5
	v_fma_f32 v32, -v4, v31, v30
	v_fmac_f32_e32 v31, v32, v5
	v_fma_f32 v4, -v4, v31, v30
	v_div_fmas_f32 v4, v4, v5, v31
	v_div_fixup_f32 v3, v4, v3, s37
	v_cndmask_b32_e64 v3, 1.0, v3, s[0:1]
	v_mul_f32_e32 v4, v26, v3
	v_mul_f32_e32 v5, v27, v3
	v_mov_b32_e32 v26, v149
	v_cvt_scalef32_pk_fp4_f32 v26, v4, v5, 1.0
	v_mul_f32_e32 v4, v28, v3
	v_mul_f32_e32 v5, v29, v3
	v_cvt_scalef32_pk_fp4_f32 v26, v4, v5, 1.0 op_sel:[0,0,1,0]
	v_mul_f32_e32 v4, v22, v3
	v_mul_f32_e32 v5, v23, v3
	v_cvt_scalef32_pk_fp4_f32 v26, v4, v5, 1.0 op_sel:[0,0,0,1]
	v_mul_f32_e32 v4, v24, v3
	v_mul_f32_e32 v5, v25, v3
	v_cvt_scalef32_pk_fp4_f32 v26, v4, v5, 1.0 op_sel:[0,0,1,1]
	v_mul_f32_e32 v4, v18, v3
	v_mul_f32_e32 v5, v19, v3
	v_mov_b32_e32 v27, v149
	v_cvt_scalef32_pk_fp4_f32 v27, v4, v5, 1.0
	v_mul_f32_e32 v4, v20, v3
	v_mul_f32_e32 v5, v21, v3
	v_cvt_scalef32_pk_fp4_f32 v27, v4, v5, 1.0 op_sel:[0,0,1,0]
	v_mul_f32_e32 v4, v14, v3
	v_mul_f32_e32 v5, v15, v3
	v_cvt_scalef32_pk_fp4_f32 v27, v4, v5, 1.0 op_sel:[0,0,0,1]
	v_mul_f32_e32 v4, v16, v3
	v_mul_f32_e32 v5, v17, v3
	v_cvt_scalef32_pk_fp4_f32 v27, v4, v5, 1.0 op_sel:[0,0,1,1]
	v_lshl_add_u64 v[4:5], s[82:83], 0, v[148:149]
	v_lshlrev_b32_e32 v148, 9, v13
	v_lshl_add_u64 v[14:15], v[4:5], 0, v[148:149]
	v_lshl_add_u64 v[14:15], v[14:15], 0, v[0:1]
	global_store_dwordx2 v[14:15], v[26:27], off
	s_and_saveexec_b64 s[0:1], s[2:3]
	s_cbranch_execz .LBB0_1192
	v_div_scale_f32 v14, s[4:5], v3, v3, 1.0
	v_rcp_f32_e32 v15, v14
	v_div_scale_f32 v16, vcc, 1.0, v3, 1.0
	v_lshlrev_b32_e32 v148, 2, v13
	v_fma_f32 v17, -v14, v15, 1.0
	v_fmac_f32_e32 v15, v17, v15
	v_mul_f32_e32 v17, v16, v15
	v_fma_f32 v18, -v14, v17, v16
	v_fmac_f32_e32 v17, v18, v15
	v_fma_f32 v14, -v14, v17, v16
	v_lshl_add_u64 v[4:5], v[4:5], 0, v[148:149]
	v_div_fmas_f32 v14, v14, v15, v17
	v_add_co_u32_e32 v4, vcc, 0x1000000, v4
	v_div_fixup_f32 v3, v14, v3, 1.0
	s_nop 0
	v_addc_co_u32_e32 v5, vcc, 0, v5, vcc
	global_store_dword v[4:5], v3, off
	s_branch .LBB0_1192
